# q-projection weight loads issued before the pointwise-output stores (loads no longer wait behind store acks)
# baseline (speedup 1.0000x reference)
; __device__ __forceinline__ unsigned pk2(float lo, float hi) { unsigned r; asm("v_cvt_pk_bf16_f32 %0, %1, %2" : "=v"(r) : "v"(lo), "v"(hi)); return r; }
; __device__ __forceinline__ float bf_lo(unsigned w) { return __uint_as_float(w << 16); }
; __device__ __forceinline__ float bf_hi(unsigned w) { return __uint_as_float(w & 0xffff0000u); }
; __device__ __forceinline__ void mixer_chunk(KP p, LAS unsigned char* lds, int l, int chunk) {
;     ...
;         const int row = c0 + 16 * w + fr, spos = s0 + 16 * w + fr;
;         const bf16_t* zr = zb + (size_t)row * DIN_P; const float* rt = (const float*)(ws + OFF_ROPE) + (size_t)row * 32;
;         const u32x2 r1 = *(const u32x2*)(zr + ZC_KR + 4 * fq), r2 = *(const u32x2*)(zr + ZC_KR + 16 + 4 * fq);
;         const f32x4 cs = *(const f32x4*)(rt + 4 * fq), sn = *(const f32x4*)(rt + 16 + 4 * fq);
;         const f32x4 k1 = (f32x4){bf_lo(r1.x), bf_hi(r1.x), bf_lo(r1.y), bf_hi(r1.y)}, k2 = (f32x4){bf_lo(r2.x), bf_hi(r2.x), bf_lo(r2.y), bf_hi(r2.y)};
;         const f32x4 o1 = k1 * cs - k2 * sn, o2 = k2 * cs + k1 * sn;
;         u32x2 ro1, ro2; ro1.x = pk2(o1[0], o1[1]); ro1.y = pk2(o1[2], o1[3]); ro2.x = pk2(o2[0], o2[1]); ro2.y = pk2(o2[2], o2[3]);
;         bf16_t* kd = (bf16_t*)(ws + OFF_K) + ((size_t)(bidx * 4) * SEQ + spos) * 96 + 64 + 4 * fq;
; #pragma unroll
;         for (int h = 0; h < 4; ++h) { *(u32x2*)(kd + (size_t)h * SEQ * 96) = ro1; *(u32x2*)(kd + (size_t)h * SEQ * 96 + 16) = ro2; }
;     }
;     __syncthreads();
.LBB0_316:
	s_or_b64 exec, exec, s[6:7]
	v_or_b32_e32 v168, s25, v217
	v_ashrrev_i32_e32 v169, 31, v168
	v_readlane_b32 s6, v252, 6
	v_lshlrev_b64 v[70:71], 11, v[168:169]
	v_readlane_b32 s7, v252, 7
	v_mov_b32_e32 v67, v1
	s_add_i32 s89, s88, s25
	v_lshl_add_u64 v[70:71], s[6:7], 0, v[70:71]
	v_lshl_add_u64 v[170:171], v[70:71], 0, v[66:67]
	v_or_b32_e32 v70, s89, v217
	s_add_i32 s6, s88, s24
	v_ashrrev_i32_e32 v71, 31, v70
	s_waitcnt lgkmcnt(0)
	v_mov_b64_e32 v[72:73], s[44:45]
	v_or_b32_e32 v76, s6, v217
	v_mad_i64_i32 v[72:73], s[6:7], v70, s65, v[72:73]
	v_lshlrev_b64 v[70:71], 7, v[70:71]
	v_lshlrev_b32_e32 v221, 2, v68
	v_lshl_add_u64 v[70:71], s[92:93], 0, v[70:71]
	v_lshl_add_u64 v[72:73], v[72:73], 0, v[66:67]
	v_lshlrev_b32_e32 v68, 4, v68
	v_mov_b32_e32 v69, v1
	global_load_dwordx2 v[78:79], v[72:73], off offset:1664
	global_load_dwordx2 v[80:81], v[72:73], off offset:1696
	v_lshl_add_u64 v[72:73], v[70:71], 0, v[68:69]
	global_load_dwordx4 v[68:71], v[72:73], off
	s_nop 0
	global_load_dwordx4 v[72:75], v[72:73], off offset:64
	s_ashr_i32 s6, s23, 3
	s_and_b32 s96, s6, -4
	s_ashr_i32 s97, s96, 31
	s_lshl_b64 s[6:7], s[96:97], 12
	v_ashrrev_i32_e32 v77, 31, v76
	s_ashr_i32 s43, s42, 31
	s_cmp_eq_u32 s46, 0
	s_waitcnt vmcnt(3)
	v_lshlrev_b32_e32 v82, 16, v78
	s_waitcnt vmcnt(2)
	v_lshlrev_b32_e32 v84, 16, v80
	v_and_b32_e32 v85, 0xffff0000, v80
	v_lshlrev_b32_e32 v80, 16, v81
	v_and_b32_e32 v81, 0xffff0000, v81
	v_and_b32_e32 v83, 0xffff0000, v78
	v_lshlrev_b32_e32 v78, 16, v79
	v_and_b32_e32 v79, 0xffff0000, v79
	s_waitcnt vmcnt(0)
	v_pk_mul_f32 v[86:87], v[74:75], v[80:81]
	v_pk_mul_f32 v[88:89], v[72:73], v[84:85]
	v_pk_fma_f32 v[86:87], v[70:71], v[78:79], v[86:87] neg_lo:[0,0,1] neg_hi:[0,0,1]
	v_pk_fma_f32 v[88:89], v[68:69], v[82:83], v[88:89] neg_lo:[0,0,1] neg_hi:[0,0,1]
	v_pk_mul_f32 v[70:71], v[70:71], v[80:81]
	v_pk_mul_f32 v[68:69], v[68:69], v[84:85]
	v_pk_fma_f32 v[70:71], v[74:75], v[78:79], v[70:71]
	v_pk_fma_f32 v[68:69], v[72:73], v[82:83], v[68:69]
	v_mov_b64_e32 v[74:75], s[12:13]
	v_cvt_pk_bf16_f32 v68, v68, v69
	v_cvt_pk_bf16_f32 v69, v70, v71
	v_lshl_add_u64 v[70:71], s[6:7], 0, v[76:77]
	v_mad_u64_u32 v[74:75], s[6:7], v70, s57, v[74:75]
	v_mad_i32_i24 v75, v71, s57, v75
	v_lshl_add_u64 v[66:67], v[74:75], 0, v[66:67]
	s_mov_b32 s6, 0xc0000
	v_add_co_u32_e32 v70, vcc, s6, v66
	v_cvt_pk_bf16_f32 v72, v88, v89
	v_cvt_pk_bf16_f32 v73, v86, v87
	s_mov_b32 s6, 0x180000
	s_nop 0
	v_addc_co_u32_e32 v71, vcc, 0, v67, vcc
	s_nop 1
	v_mov_b32_e32 v244, v72
	v_mov_b32_e32 v245, v73
	v_mov_b32_e32 v246, v68
	v_mov_b32_e32 v247, v69
	v_bfe_u32 v248, v193, 4, 1
	v_mul_u32_u24_e32 v248, 24, v248
	v_add_co_u32_e64 v248, s[98:99], v248, v66
	s_nop 1
	v_addc_co_u32_e64 v249, s[98:99], 0, v67, s[98:99]
	v_permlane16_swap_b32_e32 v244, v246
	v_permlane16_swap_b32_e32 v245, v247
	global_store_dwordx4 v[248:249], v[244:247], off offset:128
	s_nop 1
	v_mov_b32_e32 v244, v72
	v_mov_b32_e32 v245, v73
	v_mov_b32_e32 v246, v68
	v_mov_b32_e32 v247, v69
	v_bfe_u32 v248, v193, 4, 1
	v_mul_u32_u24_e32 v248, 24, v248
	v_add_co_u32_e64 v248, s[98:99], v248, v70
	s_nop 1
	v_addc_co_u32_e64 v249, s[98:99], 0, v71, s[98:99]
	v_permlane16_swap_b32_e32 v244, v246
	v_permlane16_swap_b32_e32 v245, v247
	global_store_dwordx4 v[248:249], v[244:247], off offset:128
	v_add_co_u32_e32 v70, vcc, s6, v66
	s_mov_b32 s6, 0x240000
	s_nop 0
	v_addc_co_u32_e32 v71, vcc, 0, v67, vcc
	v_add_co_u32_e32 v66, vcc, s6, v66
	s_nop 1
	v_mov_b32_e32 v244, v72
	v_mov_b32_e32 v245, v73
	v_mov_b32_e32 v246, v68
	v_mov_b32_e32 v247, v69
	v_bfe_u32 v248, v193, 4, 1
	v_mul_u32_u24_e32 v248, 24, v248
	v_add_co_u32_e64 v248, s[98:99], v248, v70
	s_nop 1
	v_addc_co_u32_e64 v249, s[98:99], 0, v71, s[98:99]
	v_permlane16_swap_b32_e32 v244, v246
	v_permlane16_swap_b32_e32 v245, v247
	global_store_dwordx4 v[248:249], v[244:247], off offset:128
	v_addc_co_u32_e32 v67, vcc, 0, v67, vcc
	s_nop 1
	v_mov_b32_e32 v244, v72
	v_mov_b32_e32 v245, v73
	v_mov_b32_e32 v246, v68
	v_mov_b32_e32 v247, v69
	v_bfe_u32 v248, v193, 4, 1
	v_mul_u32_u24_e32 v248, 24, v248
	v_add_co_u32_e64 v248, s[98:99], v248, v66
	s_nop 1
	v_addc_co_u32_e64 v249, s[98:99], 0, v67, s[98:99]
	v_permlane16_swap_b32_e32 v244, v246
	v_permlane16_swap_b32_e32 v245, v247
	global_store_dwordx4 v[248:249], v[244:247], off offset:128
	s_barrier
; #define LAS __attribute__((address_space(3)))
; __device__ __forceinline__ unsigned pk2(float lo, float hi) { unsigned r; asm("v_cvt_pk_bf16_f32 %0, %1, %2" : "=v"(r) : "v"(lo), "v"(hi)); return r; }
; __device__ __forceinline__ float rsq(float x) { return __builtin_amdgcn_rsqf(x); }
; template <int NKS, int NNT>
; __device__ __forceinline__ void wgemm(f32x4 (&acc)[8][NNT], const LAS bf16_t* A, const int lda, const bf16_t* Bp, const int ldb) {
;     u32x4 bf[NNT][NKS];
; #pragma unroll
;     for (int nt = 0; nt < NNT; ++nt) ldfr(bf[nt], Bp + (size_t)(16 * nt) * ldb);
; #pragma unroll
;     for (int nt = 0; nt < NNT; ++nt) pin(bf[nt]);
; template <int NNT>
; __device__ __forceinline__ void norm_store(const f32x4 (&acc)[8][NNT], const LAS float* part, bf16_t* dst, int fr) {
; #pragma unroll
;     for (int mt = 0; mt < 8; ++mt) {
;         const LAS f32x4* pp = (const LAS f32x4*)(part + (16 * mt + fr) * 8); const f32x4 a = pp[0], b = pp[1];
;         const float rs = rsq((((a[0] + a[1]) + (a[2] + a[3])) + ((b[0] + b[1]) + (b[2] + b[3]))) * (1.0f / 256.0f) + EPS);
; #pragma unroll
;         for (int nt = 0; nt < NNT; ++nt) { u32x2 o; o.x = pk2(acc[mt][nt][0] * rs, acc[mt][nt][1] * rs); o.y = pk2(acc[mt][nt][2] * rs, acc[mt][nt][3] * rs);
;             *(u32x2*)(dst + (size_t)(16 * mt) * DM + 16 * nt) = o; }
;     }
; }
	s_mul_i32 s100, s55, 48
	v_or_b32_e32 v158, s100, v217
	v_mul_u32_u24_e32 v158, 0x180, v158
	v_and_b32_e32 v159, 48, v205
	v_add_u32_e32 v158, v158, v159
	v_add_u32_e32 v159, 0x1800, v158
	v_add_u32_e32 v160, 0x3000, v158
	global_load_dwordx4 v[154:157], v158, s[10:11]
	global_load_dwordx4 v[150:153], v158, s[10:11] offset:64
	global_load_dwordx4 v[142:145], v158, s[10:11] offset:128
	global_load_dwordx4 v[138:141], v158, s[10:11] offset:192
	global_load_dwordx4 v[172:175], v158, s[10:11] offset:256
	global_load_dwordx4 v[176:179], v158, s[10:11] offset:320
	global_load_dwordx4 v[180:183], v159, s[10:11]
	global_load_dwordx4 v[98:101], v159, s[10:11] offset:64
	global_load_dwordx4 v[102:105], v159, s[10:11] offset:128
	global_load_dwordx4 v[106:109], v159, s[10:11] offset:192
	global_load_dwordx4 v[110:113], v159, s[10:11] offset:256
	global_load_dwordx4 v[114:117], v159, s[10:11] offset:320
	global_load_dwordx4 v[146:149], v160, s[10:11]
	global_load_dwordx4 v[118:121], v160, s[10:11] offset:64
	global_load_dwordx4 v[122:125], v160, s[10:11] offset:128
	global_load_dwordx4 v[126:129], v160, s[10:11] offset:192
	global_load_dwordx4 v[130:133], v160, s[10:11] offset:256
	global_load_dwordx4 v[134:137], v160, s[10:11] offset:320
	ds_read_b128 v[68:71], v215
	ds_read_b128 v[72:75], v215 offset:16
	v_lshl_add_u64 v[66:67], s[42:43], 1, v[170:171]
	s_mov_b32 s6, 0x8000
	s_cselect_b64 s[42:43], -1, 0
	s_waitcnt lgkmcnt(1)
	v_mov_b32_e32 v76, v68
	s_waitcnt lgkmcnt(0)
	v_mov_b32_e32 v77, v72
	v_mov_b32_e32 v72, v69
	v_pk_add_f32 v[68:69], v[76:77], v[72:73]
	v_mov_b32_e32 v72, v70
	v_mov_b32_e32 v73, v74
	v_mov_b32_e32 v74, v71
	v_pk_add_f32 v[70:71], v[72:73], v[74:75]
	s_cmp_lg_u32 s46, 0
	v_pk_add_f32 v[68:69], v[68:69], v[70:71]
	s_cselect_b64 s[90:91], -1, 0
	v_add_f32_e32 v68, v68, v69
	v_fmamk_f32 v68, v68, 0x3b800000, v189
	v_rsq_f32_e32 v68, v68
	s_nop 0
	v_mul_f32_e32 v62, v62, v68
	v_mul_f32_e32 v63, v63, v68
	v_mul_f32_e32 v58, v58, v68
	v_mul_f32_e32 v59, v59, v68
	v_cvt_pk_bf16_f32 v62, v62, v63
	v_mul_f32_e32 v63, v64, v68
	v_cvt_pk_bf16_f32 v58, v58, v59
	v_mul_f32_e32 v59, v60, v68
	v_mul_f32_e32 v64, v65, v68
	v_cvt_pk_bf16_f32 v63, v63, v64
	s_nop 1
	v_mov_b32_e32 v244, v62
	v_mov_b32_e32 v245, v63
	v_mul_f32_e32 v60, v61, v68
	v_cvt_pk_bf16_f32 v59, v59, v60
	v_mov_b32_e32 v246, v58
	v_mov_b32_e32 v247, v59
	v_bfe_u32 v248, v193, 4, 1
	v_mul_u32_u24_e32 v248, 24, v248
	v_add_co_u32_e64 v248, s[98:99], v248, v66
	s_nop 1
	v_addc_co_u32_e64 v249, s[98:99], 0, v67, s[98:99]
	v_permlane16_swap_b32_e32 v244, v246
	v_permlane16_swap_b32_e32 v245, v247
	global_store_dwordx4 v[248:249], v[244:247], off
	ds_read_b128 v[58:61], v215 offset:512
	ds_read_b128 v[62:65], v215 offset:528
	s_waitcnt lgkmcnt(1)
	v_mov_b32_e32 v68, v58
	s_waitcnt lgkmcnt(0)
	v_mov_b32_e32 v69, v62
	v_mov_b32_e32 v62, v59
	v_pk_add_f32 v[58:59], v[68:69], v[62:63]
	v_mov_b32_e32 v62, v60
	v_mov_b32_e32 v63, v64
	v_mov_b32_e32 v64, v61
	v_pk_add_f32 v[60:61], v[62:63], v[64:65]
	s_nop 0
	v_pk_add_f32 v[58:59], v[58:59], v[60:61]
	s_nop 0
	v_add_f32_e32 v58, v58, v59
	v_fmamk_f32 v58, v58, 0x3b800000, v189
	v_rsq_f32_e32 v58, v58
	s_nop 0
	v_mul_f32_e32 v54, v54, v58
	v_mul_f32_e32 v55, v55, v58
	v_cvt_pk_bf16_f32 v54, v54, v55
	v_mul_f32_e32 v55, v56, v58
	v_mul_f32_e32 v56, v57, v58
	v_cvt_pk_bf16_f32 v55, v55, v56
	v_add_co_u32_e32 v56, vcc, s6, v66
	v_mul_f32_e32 v50, v50, v58
	v_mul_f32_e32 v51, v51, v58
	v_addc_co_u32_e32 v57, vcc, 0, v67, vcc
	v_cvt_pk_bf16_f32 v50, v50, v51
	v_mul_f32_e32 v51, v52, v58
	s_nop 1
	v_mov_b32_e32 v244, v54
	v_mov_b32_e32 v245, v55
	v_mul_f32_e32 v52, v53, v58
	v_cvt_pk_bf16_f32 v51, v51, v52
	v_mov_b32_e32 v246, v50
	v_mov_b32_e32 v247, v51
	v_bfe_u32 v248, v193, 4, 1
	v_mul_u32_u24_e32 v248, 24, v248
	v_add_co_u32_e64 v248, s[98:99], v248, v56
	s_nop 1
	v_addc_co_u32_e64 v249, s[98:99], 0, v57, s[98:99]
	v_permlane16_swap_b32_e32 v244, v246
	v_permlane16_swap_b32_e32 v245, v247
	global_store_dwordx4 v[248:249], v[244:247], off
	ds_read_b128 v[50:53], v215 offset:1024
	ds_read_b128 v[54:57], v215 offset:1040
	s_mov_b32 s6, 0x18000
	s_waitcnt lgkmcnt(1)
	v_mov_b32_e32 v58, v50
	s_waitcnt lgkmcnt(0)
	v_mov_b32_e32 v59, v54
	v_mov_b32_e32 v54, v51
	v_pk_add_f32 v[50:51], v[58:59], v[54:55]
	v_mov_b32_e32 v54, v52
	v_mov_b32_e32 v55, v56
	v_mov_b32_e32 v56, v53
	v_pk_add_f32 v[52:53], v[54:55], v[56:57]
	s_nop 0
	v_pk_add_f32 v[50:51], v[50:51], v[52:53]
	s_nop 0
	v_add_f32_e32 v50, v50, v51
	v_fmamk_f32 v50, v50, 0x3b800000, v189
	v_rsq_f32_e32 v50, v50
	s_nop 0
	v_mul_f32_e32 v46, v46, v50
	v_mul_f32_e32 v47, v47, v50
	v_cvt_pk_bf16_f32 v46, v46, v47
	v_mul_f32_e32 v47, v48, v50
	v_mul_f32_e32 v48, v49, v50
	v_cvt_pk_bf16_f32 v47, v47, v48
	v_add_co_u32_e32 v48, vcc, s72, v66
	v_mul_f32_e32 v42, v42, v50
	v_mul_f32_e32 v43, v43, v50
	v_addc_co_u32_e32 v49, vcc, 0, v67, vcc
	v_cvt_pk_bf16_f32 v42, v42, v43
	v_mul_f32_e32 v43, v44, v50
	s_nop 1
	v_mov_b32_e32 v244, v46
	v_mov_b32_e32 v245, v47
	v_mul_f32_e32 v44, v45, v50
	v_cvt_pk_bf16_f32 v43, v43, v44
	v_mov_b32_e32 v246, v42
	v_mov_b32_e32 v247, v43
	v_bfe_u32 v248, v193, 4, 1
	v_mul_u32_u24_e32 v248, 24, v248
	v_add_co_u32_e64 v248, s[98:99], v248, v48
	s_nop 1
	v_addc_co_u32_e64 v249, s[98:99], 0, v49, s[98:99]
	v_permlane16_swap_b32_e32 v244, v246
	v_permlane16_swap_b32_e32 v245, v247
	global_store_dwordx4 v[248:249], v[244:247], off
	ds_read_b128 v[42:45], v215 offset:1536
	ds_read_b128 v[46:49], v215 offset:1552
	s_waitcnt lgkmcnt(1)
	v_mov_b32_e32 v50, v42
	s_waitcnt lgkmcnt(0)
; #define LAS __attribute__((address_space(3)))
; __device__ __forceinline__ unsigned pk2(float lo, float hi) { unsigned r; asm("v_cvt_pk_bf16_f32 %0, %1, %2" : "=v"(r) : "v"(lo), "v"(hi)); return r; }
; __device__ __forceinline__ float rsq(float x) { return __builtin_amdgcn_rsqf(x); }
; template <int NNT>
; __device__ __forceinline__ void norm_store(const f32x4 (&acc)[8][NNT], const LAS float* part, bf16_t* dst, int fr) {
; #pragma unroll
;     for (int mt = 0; mt < 8; ++mt) {
;         const LAS f32x4* pp = (const LAS f32x4*)(part + (16 * mt + fr) * 8); const f32x4 a = pp[0], b = pp[1];
;         const float rs = rsq((((a[0] + a[1]) + (a[2] + a[3])) + ((b[0] + b[1]) + (b[2] + b[3]))) * (1.0f / 256.0f) + EPS);
; #pragma unroll
;         for (int nt = 0; nt < NNT; ++nt) { u32x2 o; o.x = pk2(acc[mt][nt][0] * rs, acc[mt][nt][1] * rs); o.y = pk2(acc[mt][nt][2] * rs, acc[mt][nt][3] * rs);
;             *(u32x2*)(dst + (size_t)(16 * mt) * DM + 16 * nt) = o; }
;     }
; }
	v_mov_b32_e32 v51, v46
	v_mov_b32_e32 v46, v43
	v_pk_add_f32 v[42:43], v[50:51], v[46:47]
	v_mov_b32_e32 v46, v44
	v_mov_b32_e32 v47, v48
	v_mov_b32_e32 v48, v45
	v_pk_add_f32 v[44:45], v[46:47], v[48:49]
	s_nop 0
	v_pk_add_f32 v[42:43], v[42:43], v[44:45]
	s_nop 0
	v_add_f32_e32 v42, v42, v43
	v_fmamk_f32 v42, v42, 0x3b800000, v189
	v_rsq_f32_e32 v42, v42
	s_nop 0
	v_mul_f32_e32 v38, v38, v42
	v_mul_f32_e32 v39, v39, v42
	v_cvt_pk_bf16_f32 v38, v38, v39
	v_mul_f32_e32 v39, v40, v42
	v_mul_f32_e32 v40, v41, v42
	v_cvt_pk_bf16_f32 v39, v39, v40
	v_add_co_u32_e32 v40, vcc, s6, v66
	v_mul_f32_e32 v34, v34, v42
	v_mul_f32_e32 v35, v35, v42
	v_addc_co_u32_e32 v41, vcc, 0, v67, vcc
	v_cvt_pk_bf16_f32 v34, v34, v35
	v_mul_f32_e32 v35, v36, v42
	s_nop 1
	v_mov_b32_e32 v244, v38
	v_mov_b32_e32 v245, v39
	v_mul_f32_e32 v36, v37, v42
	v_cvt_pk_bf16_f32 v35, v35, v36
	v_mov_b32_e32 v246, v34
	v_mov_b32_e32 v247, v35
	v_bfe_u32 v248, v193, 4, 1
	v_mul_u32_u24_e32 v248, 24, v248
	v_add_co_u32_e64 v248, s[98:99], v248, v40
	s_nop 1
	v_addc_co_u32_e64 v249, s[98:99], 0, v41, s[98:99]
	v_permlane16_swap_b32_e32 v244, v246
	v_permlane16_swap_b32_e32 v245, v247
	global_store_dwordx4 v[248:249], v[244:247], off
	ds_read_b128 v[34:37], v215 offset:2048
	ds_read_b128 v[38:41], v215 offset:2064
	s_mov_b32 s6, 0x20000
	s_waitcnt lgkmcnt(1)
	v_mov_b32_e32 v42, v34
	s_waitcnt lgkmcnt(0)
	v_mov_b32_e32 v43, v38
	v_mov_b32_e32 v38, v35
	v_pk_add_f32 v[34:35], v[42:43], v[38:39]
	v_mov_b32_e32 v38, v36
	v_mov_b32_e32 v39, v40
	v_mov_b32_e32 v40, v37
	v_pk_add_f32 v[36:37], v[38:39], v[40:41]
	s_nop 0
	v_pk_add_f32 v[34:35], v[34:35], v[36:37]
	s_nop 0
	v_add_f32_e32 v34, v34, v35
	v_fmamk_f32 v34, v34, 0x3b800000, v189
	v_rsq_f32_e32 v34, v34
	s_nop 0
	v_mul_f32_e32 v30, v30, v34
	v_mul_f32_e32 v31, v31, v34
	v_cvt_pk_bf16_f32 v30, v30, v31
	v_mul_f32_e32 v31, v32, v34
	v_mul_f32_e32 v32, v33, v34
	v_cvt_pk_bf16_f32 v31, v31, v32
	v_add_co_u32_e32 v32, vcc, s6, v66
	v_mul_f32_e32 v26, v26, v34
	v_mul_f32_e32 v27, v27, v34
	v_addc_co_u32_e32 v33, vcc, 0, v67, vcc
	v_cvt_pk_bf16_f32 v26, v26, v27
	v_mul_f32_e32 v27, v28, v34
	s_nop 1
	v_mov_b32_e32 v244, v30
	v_mov_b32_e32 v245, v31
	v_mul_f32_e32 v28, v29, v34
	v_cvt_pk_bf16_f32 v27, v27, v28
	v_mov_b32_e32 v246, v26
	v_mov_b32_e32 v247, v27
	v_bfe_u32 v248, v193, 4, 1
	v_mul_u32_u24_e32 v248, 24, v248
	v_add_co_u32_e64 v248, s[98:99], v248, v32
	s_nop 1
	v_addc_co_u32_e64 v249, s[98:99], 0, v33, s[98:99]
	v_permlane16_swap_b32_e32 v244, v246
	v_permlane16_swap_b32_e32 v245, v247
	global_store_dwordx4 v[248:249], v[244:247], off
	ds_read_b128 v[26:29], v215 offset:2560
	ds_read_b128 v[30:33], v215 offset:2576
	s_mov_b32 s6, 0x28000
	s_waitcnt lgkmcnt(1)
	v_mov_b32_e32 v34, v26
	s_waitcnt lgkmcnt(0)
	v_mov_b32_e32 v35, v30
	v_mov_b32_e32 v30, v27
	v_pk_add_f32 v[26:27], v[34:35], v[30:31]
	v_mov_b32_e32 v30, v28
	v_mov_b32_e32 v31, v32
	v_mov_b32_e32 v32, v29
	v_pk_add_f32 v[28:29], v[30:31], v[32:33]
	s_nop 0
	v_pk_add_f32 v[26:27], v[26:27], v[28:29]
	s_nop 0
	v_add_f32_e32 v26, v26, v27
	v_fmamk_f32 v26, v26, 0x3b800000, v189
	v_rsq_f32_e32 v26, v26
	s_nop 0
	v_mul_f32_e32 v22, v22, v26
	v_mul_f32_e32 v23, v23, v26
	v_cvt_pk_bf16_f32 v22, v22, v23
	v_mul_f32_e32 v23, v24, v26
	v_mul_f32_e32 v24, v25, v26
	v_cvt_pk_bf16_f32 v23, v23, v24
	v_add_co_u32_e32 v24, vcc, s6, v66
	v_mul_f32_e32 v18, v18, v26
	v_mul_f32_e32 v19, v19, v26
	v_addc_co_u32_e32 v25, vcc, 0, v67, vcc
	v_cvt_pk_bf16_f32 v18, v18, v19
	v_mul_f32_e32 v19, v20, v26
	s_nop 1
	v_mov_b32_e32 v244, v22
	v_mov_b32_e32 v245, v23
	v_mul_f32_e32 v20, v21, v26
	v_cvt_pk_bf16_f32 v19, v19, v20
	v_mov_b32_e32 v246, v18
	v_mov_b32_e32 v247, v19
	v_bfe_u32 v248, v193, 4, 1
	v_mul_u32_u24_e32 v248, 24, v248
	v_add_co_u32_e64 v248, s[98:99], v248, v24
	s_nop 1
	v_addc_co_u32_e64 v249, s[98:99], 0, v25, s[98:99]
	v_permlane16_swap_b32_e32 v244, v246
	v_permlane16_swap_b32_e32 v245, v247
	global_store_dwordx4 v[248:249], v[244:247], off
	ds_read_b128 v[18:21], v215 offset:3072
	ds_read_b128 v[22:25], v215 offset:3088
	s_mov_b32 s6, 0x30000
	s_waitcnt lgkmcnt(1)
	v_mov_b32_e32 v26, v18
	s_waitcnt lgkmcnt(0)
	v_mov_b32_e32 v27, v22
	v_mov_b32_e32 v22, v19
	v_pk_add_f32 v[18:19], v[26:27], v[22:23]
	v_mov_b32_e32 v22, v20
	v_mov_b32_e32 v23, v24
	v_mov_b32_e32 v24, v21
	v_pk_add_f32 v[20:21], v[22:23], v[24:25]
	s_nop 0
	v_pk_add_f32 v[18:19], v[18:19], v[20:21]
	s_nop 0
	v_add_f32_e32 v18, v18, v19
	v_fmamk_f32 v18, v18, 0x3b800000, v189
	v_rsq_f32_e32 v18, v18
	s_nop 0
	v_mul_f32_e32 v14, v14, v18
	v_mul_f32_e32 v15, v15, v18
	v_cvt_pk_bf16_f32 v14, v14, v15
	v_mul_f32_e32 v15, v16, v18
	v_mul_f32_e32 v16, v17, v18
	v_cvt_pk_bf16_f32 v15, v15, v16
	v_add_co_u32_e32 v16, vcc, s6, v66
	v_mul_f32_e32 v10, v10, v18
	v_mul_f32_e32 v11, v11, v18
	v_addc_co_u32_e32 v17, vcc, 0, v67, vcc
	v_cvt_pk_bf16_f32 v10, v10, v11
	v_mul_f32_e32 v11, v12, v18
	s_nop 1
	v_mov_b32_e32 v244, v14
	v_mov_b32_e32 v245, v15
	v_mul_f32_e32 v12, v13, v18
	v_cvt_pk_bf16_f32 v11, v11, v12
	v_mov_b32_e32 v246, v10
	v_mov_b32_e32 v247, v11
	v_bfe_u32 v248, v193, 4, 1
	v_mul_u32_u24_e32 v248, 24, v248
	v_add_co_u32_e64 v248, s[98:99], v248, v16
	s_nop 1
	v_addc_co_u32_e64 v249, s[98:99], 0, v17, s[98:99]
	v_permlane16_swap_b32_e32 v244, v246
	v_permlane16_swap_b32_e32 v245, v247
	global_store_dwordx4 v[248:249], v[244:247], off
	ds_read_b128 v[10:13], v215 offset:3584
	ds_read_b128 v[14:17], v215 offset:3600
	s_mov_b32 s6, 0x38000
	s_waitcnt lgkmcnt(1)
	v_mov_b32_e32 v18, v10
	s_waitcnt lgkmcnt(0)
; #define LAS __attribute__((address_space(3)))
; __device__ __forceinline__ unsigned pk2(float lo, float hi) { unsigned r; asm("v_cvt_pk_bf16_f32 %0, %1, %2" : "=v"(r) : "v"(lo), "v"(hi)); return r; }
; __device__ __forceinline__ f32x4 mfma16(bf16x8 a, bf16x8 b, f32x4 c) { return __builtin_amdgcn_mfma_f32_16x16x32_bf16(a, b, c, 0, 0, 0); }
; __device__ __forceinline__ float rsq(float x) { return __builtin_amdgcn_rsqf(x); }
; template <int NKS, int NNT>
; __device__ __forceinline__ void wgemm(f32x4 (&acc)[8][NNT], const LAS bf16_t* A, const int lda, const bf16_t* Bp, const int ldb) {
;     u32x4 bf[NNT][NKS];
; #pragma unroll
;     for (int nt = 0; nt < NNT; ++nt) ldfr(bf[nt], Bp + (size_t)(16 * nt) * ldb);
; #pragma unroll
;     for (int nt = 0; nt < NNT; ++nt) pin(bf[nt]);
; #pragma unroll
;     for (int mt = 0; mt < 8; ++mt) {
;         bf16x8 af[NKS];
; #pragma unroll
;         for (int ks = 0; ks < NKS; ++ks) af[ks] = *(const LAS bf16x8*)(A + (16 * mt) * lda + 32 * ks);
; #pragma unroll
;         for (int nt = 0; nt < NNT; ++nt) { f32x4 a = (f32x4){0.f, 0.f, 0.f, 0.f};
; #pragma unroll
;             for (int ks = 0; ks < NKS; ++ks) a = mfma16(as_bf16x8(bf[nt][ks]), af[ks], a);
;             acc[mt][nt] = a; }
;     }
; template <int NNT>
; __device__ __forceinline__ void norm_store(const f32x4 (&acc)[8][NNT], const LAS float* part, bf16_t* dst, int fr) {
; #pragma unroll
;     for (int mt = 0; mt < 8; ++mt) {
;         const LAS f32x4* pp = (const LAS f32x4*)(part + (16 * mt + fr) * 8); const f32x4 a = pp[0], b = pp[1];
;         const float rs = rsq((((a[0] + a[1]) + (a[2] + a[3])) + ((b[0] + b[1]) + (b[2] + b[3]))) * (1.0f / 256.0f) + EPS);
; #pragma unroll
;         for (int nt = 0; nt < NNT; ++nt) { u32x2 o; o.x = pk2(acc[mt][nt][0] * rs, acc[mt][nt][1] * rs); o.y = pk2(acc[mt][nt][2] * rs, acc[mt][nt][3] * rs);
;             *(u32x2*)(dst + (size_t)(16 * mt) * DM + 16 * nt) = o; }
;     }
; }
	v_mov_b32_e32 v19, v14
	v_mov_b32_e32 v14, v11
	v_pk_add_f32 v[10:11], v[18:19], v[14:15]
	v_mov_b32_e32 v14, v12
	v_mov_b32_e32 v15, v16
	v_mov_b32_e32 v16, v13
	v_pk_add_f32 v[12:13], v[14:15], v[16:17]
	s_nop 0
	v_pk_add_f32 v[10:11], v[10:11], v[12:13]
	s_nop 0
	v_add_f32_e32 v10, v10, v11
	v_fmamk_f32 v10, v10, 0x3b800000, v189
	v_rsq_f32_e32 v10, v10
	s_nop 0
	v_mul_f32_e32 v2, v2, v10
	v_mul_f32_e32 v3, v3, v10
	v_cvt_pk_bf16_f32 v2, v2, v3
	v_mul_f32_e32 v3, v4, v10
	v_mul_f32_e32 v4, v5, v10
	v_cvt_pk_bf16_f32 v3, v3, v4
	v_add_co_u32_e32 v4, vcc, s6, v66
	s_mul_i32 s6, s55, 48
	s_nop 0
	v_addc_co_u32_e32 v5, vcc, 0, v67, vcc
	s_nop 1
	v_mov_b32_e32 v244, v2
	v_mov_b32_e32 v245, v3
	v_mul_f32_e32 v2, v6, v10
	v_mul_f32_e32 v3, v7, v10
	v_cvt_pk_bf16_f32 v2, v2, v3
	v_mul_f32_e32 v3, v8, v10
	v_mul_f32_e32 v6, v9, v10
	v_cvt_pk_bf16_f32 v3, v3, v6
	v_mov_b32_e32 v246, v2
	v_mov_b32_e32 v247, v3
	v_bfe_u32 v248, v193, 4, 1
	v_mul_u32_u24_e32 v248, 24, v248
	v_add_co_u32_e64 v248, s[98:99], v248, v4
	s_nop 1
	v_addc_co_u32_e64 v249, s[98:99], 0, v5, s[98:99]
	v_permlane16_swap_b32_e32 v244, v246
	v_permlane16_swap_b32_e32 v245, v247
	global_store_dwordx4 v[248:249], v[244:247], off
	v_mul_u32_u24_e32 v2, 0x190, v217
	v_add3_u32 v162, 0, v2, v0
	v_or_b32_e32 v4, s6, v217
	v_mov_b64_e32 v[2:3], s[10:11]
	s_movk_i32 s6, 0x180
	v_mad_i64_i32 v[2:3], s[6:7], v4, s6, v[2:3]
	v_lshl_add_u64 v[10:11], v[2:3], 0, v[0:1]
	s_movk_i32 s6, 0x1000
	v_add_co_u32_e32 v12, vcc, s6, v10
	v_addc_co_u32_e32 v13, vcc, 0, v11, vcc
	v_add_co_u32_e32 v10, vcc, s68, v10
	v_addc_co_u32_e32 v11, vcc, 0, v11, vcc
	s_waitcnt vmcnt(8)
	v_mov_b64_e32 v[6:7], v[172:173]
	v_mov_b64_e32 v[8:9], v[174:175]
	v_mov_b64_e32 v[2:3], v[176:177]
	v_mov_b64_e32 v[4:5], v[178:179]
	v_mov_b64_e32 v[22:23], v[180:181]
	v_mov_b64_e32 v[24:25], v[182:183]
	s_waitcnt vmcnt(8)
	s_waitcnt vmcnt(8)
	ds_read_b128 v[10:13], v162
	ds_read_b128 v[14:17], v162 offset:64
	ds_read_b128 v[18:21], v162 offset:128
	ds_read_b128 v[26:29], v162 offset:192
	ds_read_b128 v[30:33], v162 offset:256
	ds_read_b128 v[34:37], v162 offset:320
	s_waitcnt lgkmcnt(5)
	v_mfma_f32_16x16x32_bf16 v[38:41], v[154:157], v[10:13], 0
	s_and_b64 vcc, exec, s[42:43]
	s_waitcnt lgkmcnt(4)
	v_mfma_f32_16x16x32_bf16 v[38:41], v[150:153], v[14:17], v[38:41]
	s_waitcnt lgkmcnt(3)
	v_mfma_f32_16x16x32_bf16 v[38:41], v[142:145], v[18:21], v[38:41]
	s_waitcnt lgkmcnt(2)
	v_mfma_f32_16x16x32_bf16 v[38:41], v[138:141], v[26:29], v[38:41]
	s_waitcnt lgkmcnt(1)
	v_mfma_f32_16x16x32_bf16 v[38:41], v[6:9], v[30:33], v[38:41]
	s_waitcnt lgkmcnt(0)
	v_mfma_f32_16x16x32_bf16 v[82:85], v[2:5], v[34:37], v[38:41]
	v_mfma_f32_16x16x32_bf16 v[38:41], v[22:25], v[10:13], 0
	v_mfma_f32_16x16x32_bf16 v[10:13], v[146:149], v[10:13], 0
	v_mfma_f32_16x16x32_bf16 v[38:41], v[98:101], v[14:17], v[38:41]
	v_mfma_f32_16x16x32_bf16 v[10:13], v[118:121], v[14:17], v[10:13]
	v_mfma_f32_16x16x32_bf16 v[38:41], v[102:105], v[18:21], v[38:41]
	v_mfma_f32_16x16x32_bf16 v[10:13], v[122:125], v[18:21], v[10:13]
	v_mfma_f32_16x16x32_bf16 v[38:41], v[106:109], v[26:29], v[38:41]
	v_mfma_f32_16x16x32_bf16 v[10:13], v[126:129], v[26:29], v[10:13]
	v_mfma_f32_16x16x32_bf16 v[38:41], v[110:113], v[30:33], v[38:41]
	v_mfma_f32_16x16x32_bf16 v[10:13], v[130:133], v[30:33], v[10:13]
	v_mfma_f32_16x16x32_bf16 v[90:93], v[114:117], v[34:37], v[38:41]
	v_mfma_f32_16x16x32_bf16 v[94:97], v[134:137], v[34:37], v[10:13]
	s_nop 5
	ds_read_b128 v[10:13], v162 offset:6400
	ds_read_b128 v[14:17], v162 offset:6464
	ds_read_b128 v[18:21], v162 offset:6528
	ds_read_b128 v[26:29], v162 offset:6592
	ds_read_b128 v[30:33], v162 offset:6656
	ds_read_b128 v[34:37], v162 offset:6720
	s_waitcnt lgkmcnt(5)
	v_mfma_f32_16x16x32_bf16 v[38:41], v[154:157], v[10:13], 0
	s_waitcnt lgkmcnt(4)
	v_mfma_f32_16x16x32_bf16 v[38:41], v[150:153], v[14:17], v[38:41]
	s_waitcnt lgkmcnt(3)
	v_mfma_f32_16x16x32_bf16 v[38:41], v[142:145], v[18:21], v[38:41]
	s_waitcnt lgkmcnt(2)
	v_mfma_f32_16x16x32_bf16 v[38:41], v[138:141], v[26:29], v[38:41]
	s_waitcnt lgkmcnt(1)
	v_mfma_f32_16x16x32_bf16 v[38:41], v[6:9], v[30:33], v[38:41]
	s_waitcnt lgkmcnt(0)
	v_mfma_f32_16x16x32_bf16 v[74:77], v[2:5], v[34:37], v[38:41]
	v_mfma_f32_16x16x32_bf16 v[38:41], v[22:25], v[10:13], 0
	v_mfma_f32_16x16x32_bf16 v[10:13], v[146:149], v[10:13], 0
	v_mfma_f32_16x16x32_bf16 v[38:41], v[98:101], v[14:17], v[38:41]
	v_mfma_f32_16x16x32_bf16 v[10:13], v[118:121], v[14:17], v[10:13]
	v_mfma_f32_16x16x32_bf16 v[38:41], v[102:105], v[18:21], v[38:41]
	v_mfma_f32_16x16x32_bf16 v[10:13], v[122:125], v[18:21], v[10:13]
	v_mfma_f32_16x16x32_bf16 v[38:41], v[106:109], v[26:29], v[38:41]
	v_mfma_f32_16x16x32_bf16 v[10:13], v[126:129], v[26:29], v[10:13]
	v_mfma_f32_16x16x32_bf16 v[38:41], v[110:113], v[30:33], v[38:41]
	v_mfma_f32_16x16x32_bf16 v[10:13], v[130:133], v[30:33], v[10:13]
	v_mfma_f32_16x16x32_bf16 v[78:81], v[114:117], v[34:37], v[38:41]
	v_mfma_f32_16x16x32_bf16 v[86:89], v[134:137], v[34:37], v[10:13]
	s_nop 5
	ds_read_b128 v[10:13], v162 offset:12800
	ds_read_b128 v[14:17], v162 offset:12864
	ds_read_b128 v[18:21], v162 offset:12928
	ds_read_b128 v[26:29], v162 offset:12992
	ds_read_b128 v[30:33], v162 offset:13056
	ds_read_b128 v[34:37], v162 offset:13120
	s_waitcnt lgkmcnt(5)
	v_mfma_f32_16x16x32_bf16 v[38:41], v[154:157], v[10:13], 0
	s_waitcnt lgkmcnt(4)
	v_mfma_f32_16x16x32_bf16 v[38:41], v[150:153], v[14:17], v[38:41]
	s_waitcnt lgkmcnt(3)
	v_mfma_f32_16x16x32_bf16 v[38:41], v[142:145], v[18:21], v[38:41]
	s_waitcnt lgkmcnt(2)
	v_mfma_f32_16x16x32_bf16 v[38:41], v[138:141], v[26:29], v[38:41]
	s_waitcnt lgkmcnt(1)
; #define LAS __attribute__((address_space(3)))
; __device__ __forceinline__ f32x4 mfma16(bf16x8 a, bf16x8 b, f32x4 c) { return __builtin_amdgcn_mfma_f32_16x16x32_bf16(a, b, c, 0, 0, 0); }
; template <int NKS, int NNT>
; __device__ __forceinline__ void wgemm(f32x4 (&acc)[8][NNT], const LAS bf16_t* A, const int lda, const bf16_t* Bp, const int ldb) {
;     ...
; #pragma unroll
;     for (int mt = 0; mt < 8; ++mt) {
;         bf16x8 af[NKS];
; #pragma unroll
;         for (int ks = 0; ks < NKS; ++ks) af[ks] = *(const LAS bf16x8*)(A + (16 * mt) * lda + 32 * ks);
; #pragma unroll
;         for (int nt = 0; nt < NNT; ++nt) { f32x4 a = (f32x4){0.f, 0.f, 0.f, 0.f};
; #pragma unroll
;             for (int ks = 0; ks < NKS; ++ks) a = mfma16(as_bf16x8(bf[nt][ks]), af[ks], a);
;             acc[mt][nt] = a; }
;     }
	v_mfma_f32_16x16x32_bf16 v[38:41], v[6:9], v[30:33], v[38:41]
	s_waitcnt lgkmcnt(0)
	v_mfma_f32_16x16x32_bf16 v[62:65], v[2:5], v[34:37], v[38:41]
	v_mfma_f32_16x16x32_bf16 v[38:41], v[22:25], v[10:13], 0
	v_mfma_f32_16x16x32_bf16 v[10:13], v[146:149], v[10:13], 0
	v_mfma_f32_16x16x32_bf16 v[38:41], v[98:101], v[14:17], v[38:41]
	v_mfma_f32_16x16x32_bf16 v[10:13], v[118:121], v[14:17], v[10:13]
	v_mfma_f32_16x16x32_bf16 v[38:41], v[102:105], v[18:21], v[38:41]
	v_mfma_f32_16x16x32_bf16 v[10:13], v[122:125], v[18:21], v[10:13]
	v_mfma_f32_16x16x32_bf16 v[38:41], v[106:109], v[26:29], v[38:41]
	v_mfma_f32_16x16x32_bf16 v[10:13], v[126:129], v[26:29], v[10:13]
	v_mfma_f32_16x16x32_bf16 v[38:41], v[110:113], v[30:33], v[38:41]
	v_mfma_f32_16x16x32_bf16 v[10:13], v[130:133], v[30:33], v[10:13]
	v_mfma_f32_16x16x32_bf16 v[66:69], v[114:117], v[34:37], v[38:41]
	v_mfma_f32_16x16x32_bf16 v[70:73], v[134:137], v[34:37], v[10:13]
	s_nop 5
	ds_read_b128 v[10:13], v162 offset:19200
	ds_read_b128 v[14:17], v162 offset:19264
	ds_read_b128 v[18:21], v162 offset:19328
	ds_read_b128 v[26:29], v162 offset:19392
	ds_read_b128 v[30:33], v162 offset:19456
	ds_read_b128 v[34:37], v162 offset:19520
	s_waitcnt lgkmcnt(5)
	v_mfma_f32_16x16x32_bf16 v[38:41], v[154:157], v[10:13], 0
	s_waitcnt lgkmcnt(4)
	v_mfma_f32_16x16x32_bf16 v[38:41], v[150:153], v[14:17], v[38:41]
	s_waitcnt lgkmcnt(3)
	v_mfma_f32_16x16x32_bf16 v[38:41], v[142:145], v[18:21], v[38:41]
	s_waitcnt lgkmcnt(2)
	v_mfma_f32_16x16x32_bf16 v[38:41], v[138:141], v[26:29], v[38:41]
	s_waitcnt lgkmcnt(1)
	v_mfma_f32_16x16x32_bf16 v[38:41], v[6:9], v[30:33], v[38:41]
	s_waitcnt lgkmcnt(0)
	v_mfma_f32_16x16x32_bf16 v[50:53], v[2:5], v[34:37], v[38:41]
	v_mfma_f32_16x16x32_bf16 v[38:41], v[22:25], v[10:13], 0
	v_mfma_f32_16x16x32_bf16 v[10:13], v[146:149], v[10:13], 0
	v_mfma_f32_16x16x32_bf16 v[38:41], v[98:101], v[14:17], v[38:41]
	v_mfma_f32_16x16x32_bf16 v[10:13], v[118:121], v[14:17], v[10:13]
	v_mfma_f32_16x16x32_bf16 v[38:41], v[102:105], v[18:21], v[38:41]
	v_mfma_f32_16x16x32_bf16 v[10:13], v[122:125], v[18:21], v[10:13]
	v_mfma_f32_16x16x32_bf16 v[38:41], v[106:109], v[26:29], v[38:41]
	v_mfma_f32_16x16x32_bf16 v[10:13], v[126:129], v[26:29], v[10:13]
	v_mfma_f32_16x16x32_bf16 v[38:41], v[110:113], v[30:33], v[38:41]
	v_mfma_f32_16x16x32_bf16 v[10:13], v[130:133], v[30:33], v[10:13]
	v_mfma_f32_16x16x32_bf16 v[54:57], v[114:117], v[34:37], v[38:41]
	v_mfma_f32_16x16x32_bf16 v[58:61], v[134:137], v[34:37], v[10:13]
	s_nop 5
	ds_read_b128 v[10:13], v162 offset:25600
	ds_read_b128 v[14:17], v162 offset:25664
	ds_read_b128 v[18:21], v162 offset:25728
	ds_read_b128 v[26:29], v162 offset:25792
	ds_read_b128 v[34:37], v162 offset:25856
	ds_read_b128 v[42:45], v162 offset:25920
	s_waitcnt lgkmcnt(5)
	v_mfma_f32_16x16x32_bf16 v[30:33], v[154:157], v[10:13], 0
	v_mfma_f32_16x16x32_bf16 v[38:41], v[22:25], v[10:13], 0
	v_mfma_f32_16x16x32_bf16 v[10:13], v[146:149], v[10:13], 0
	s_waitcnt lgkmcnt(4)
	v_mfma_f32_16x16x32_bf16 v[30:33], v[150:153], v[14:17], v[30:33]
	v_mfma_f32_16x16x32_bf16 v[38:41], v[98:101], v[14:17], v[38:41]
	v_mfma_f32_16x16x32_bf16 v[10:13], v[118:121], v[14:17], v[10:13]
	s_waitcnt lgkmcnt(3)
	v_mfma_f32_16x16x32_bf16 v[30:33], v[142:145], v[18:21], v[30:33]
	v_mfma_f32_16x16x32_bf16 v[38:41], v[102:105], v[18:21], v[38:41]
	v_mfma_f32_16x16x32_bf16 v[10:13], v[122:125], v[18:21], v[10:13]
	s_waitcnt lgkmcnt(2)
	v_mfma_f32_16x16x32_bf16 v[30:33], v[138:141], v[26:29], v[30:33]
	v_mfma_f32_16x16x32_bf16 v[38:41], v[106:109], v[26:29], v[38:41]
	v_mfma_f32_16x16x32_bf16 v[10:13], v[126:129], v[26:29], v[10:13]
	s_waitcnt lgkmcnt(1)
	v_mfma_f32_16x16x32_bf16 v[30:33], v[6:9], v[34:37], v[30:33]
	v_mfma_f32_16x16x32_bf16 v[38:41], v[110:113], v[34:37], v[38:41]
	v_mfma_f32_16x16x32_bf16 v[10:13], v[130:133], v[34:37], v[10:13]
	s_waitcnt lgkmcnt(0)
	v_mfma_f32_16x16x32_bf16 v[30:33], v[2:5], v[42:45], v[30:33]
	v_mfma_f32_16x16x32_bf16 v[38:41], v[114:117], v[42:45], v[38:41]
	v_mfma_f32_16x16x32_bf16 v[46:49], v[134:137], v[42:45], v[10:13]
	s_nop 3
	ds_read_b128 v[10:13], v162 offset:32000
	ds_read_b128 v[14:17], v162 offset:32064
	ds_read_b128 v[18:21], v162 offset:32128
	ds_read_b128 v[42:45], v162 offset:32192
	ds_read_b128 v[158:161], v162 offset:32256
	ds_read_b128 v[172:175], v162 offset:32320
	s_waitcnt lgkmcnt(5)
	v_mfma_f32_16x16x32_bf16 v[26:29], v[154:157], v[10:13], 0
	v_mfma_f32_16x16x32_bf16 v[34:37], v[22:25], v[10:13], 0
	v_mfma_f32_16x16x32_bf16 v[10:13], v[146:149], v[10:13], 0
	s_waitcnt lgkmcnt(4)
	v_mfma_f32_16x16x32_bf16 v[26:29], v[150:153], v[14:17], v[26:29]
	v_mfma_f32_16x16x32_bf16 v[34:37], v[98:101], v[14:17], v[34:37]
	v_mfma_f32_16x16x32_bf16 v[10:13], v[118:121], v[14:17], v[10:13]
	s_waitcnt lgkmcnt(3)
	v_mfma_f32_16x16x32_bf16 v[26:29], v[142:145], v[18:21], v[26:29]
	v_mfma_f32_16x16x32_bf16 v[34:37], v[102:105], v[18:21], v[34:37]
	v_mfma_f32_16x16x32_bf16 v[10:13], v[122:125], v[18:21], v[10:13]
	s_waitcnt lgkmcnt(2)
	v_mfma_f32_16x16x32_bf16 v[26:29], v[138:141], v[42:45], v[26:29]
	v_mfma_f32_16x16x32_bf16 v[34:37], v[106:109], v[42:45], v[34:37]
	v_mfma_f32_16x16x32_bf16 v[10:13], v[126:129], v[42:45], v[10:13]
	s_waitcnt lgkmcnt(1)
	v_mfma_f32_16x16x32_bf16 v[26:29], v[6:9], v[158:161], v[26:29]
	v_mfma_f32_16x16x32_bf16 v[34:37], v[110:113], v[158:161], v[34:37]
	v_mfma_f32_16x16x32_bf16 v[10:13], v[130:133], v[158:161], v[10:13]
	s_waitcnt lgkmcnt(0)
; #define LAS __attribute__((address_space(3)))
; __device__ __forceinline__ f32x4 mfma16(bf16x8 a, bf16x8 b, f32x4 c) { return __builtin_amdgcn_mfma_f32_16x16x32_bf16(a, b, c, 0, 0, 0); }
; template <int NKS, int NNT>
; __device__ __forceinline__ void wgemm(f32x4 (&acc)[8][NNT], const LAS bf16_t* A, const int lda, const bf16_t* Bp, const int ldb) {
;     ...
; #pragma unroll
;     for (int mt = 0; mt < 8; ++mt) {
;         bf16x8 af[NKS];
; #pragma unroll
;         for (int ks = 0; ks < NKS; ++ks) af[ks] = *(const LAS bf16x8*)(A + (16 * mt) * lda + 32 * ks);
; #pragma unroll
;         for (int nt = 0; nt < NNT; ++nt) { f32x4 a = (f32x4){0.f, 0.f, 0.f, 0.f};
; #pragma unroll
;             for (int ks = 0; ks < NKS; ++ks) a = mfma16(as_bf16x8(bf[nt][ks]), af[ks], a);
;             acc[mt][nt] = a; }
;     }
; __device__ __forceinline__ void mixer_chunk(KP p, LAS unsigned char* lds, int l, int chunk) {
;     ...
;         const int head = (3 * w) / 6, d0 = 16 * ((3 * w) % 6);
;         u32x4 csn[16];
;         if (w & 1) {
; #pragma unroll
;             for (int mt = 0; mt < 8; ++mt) { const float* rt = (const float*)(ws + OFF_ROPE) + (size_t)(c0 + 16 * mt + fr) * 32 + 4 * fq; csn[2 * mt] = *(const u32x4*)rt; csn[2 * mt + 1] = *(const u32x4*)(rt + 16); }
;             pin(csn);
;         }
	v_mfma_f32_16x16x32_bf16 v[26:29], v[2:5], v[172:175], v[26:29]
	v_mfma_f32_16x16x32_bf16 v[34:37], v[114:117], v[172:175], v[34:37]
	v_mfma_f32_16x16x32_bf16 v[42:45], v[134:137], v[172:175], v[10:13]
	ds_read_b128 v[18:21], v162 offset:38400
	ds_read_b128 v[158:161], v162 offset:38464
	ds_read_b128 v[172:175], v162 offset:38528
	ds_read_b128 v[176:179], v162 offset:38592
	ds_read_b128 v[180:183], v162 offset:38656
	ds_read_b128 v[184:187], v162 offset:38720
	s_waitcnt lgkmcnt(5)
	v_mfma_f32_16x16x32_bf16 v[10:13], v[154:157], v[18:21], 0
	v_mfma_f32_16x16x32_bf16 v[14:17], v[22:25], v[18:21], 0
	v_mfma_f32_16x16x32_bf16 v[18:21], v[146:149], v[18:21], 0
	s_waitcnt lgkmcnt(4)
	v_mfma_f32_16x16x32_bf16 v[10:13], v[150:153], v[158:161], v[10:13]
	v_mfma_f32_16x16x32_bf16 v[14:17], v[98:101], v[158:161], v[14:17]
	v_mfma_f32_16x16x32_bf16 v[18:21], v[118:121], v[158:161], v[18:21]
	s_waitcnt lgkmcnt(3)
	v_mfma_f32_16x16x32_bf16 v[10:13], v[142:145], v[172:175], v[10:13]
	v_mfma_f32_16x16x32_bf16 v[14:17], v[102:105], v[172:175], v[14:17]
	v_mfma_f32_16x16x32_bf16 v[18:21], v[122:125], v[172:175], v[18:21]
	s_waitcnt lgkmcnt(2)
	v_mfma_f32_16x16x32_bf16 v[10:13], v[138:141], v[176:179], v[10:13]
	v_mfma_f32_16x16x32_bf16 v[14:17], v[106:109], v[176:179], v[14:17]
	v_mfma_f32_16x16x32_bf16 v[18:21], v[126:129], v[176:179], v[18:21]
	s_waitcnt lgkmcnt(1)
	v_mfma_f32_16x16x32_bf16 v[10:13], v[6:9], v[180:183], v[10:13]
	v_mfma_f32_16x16x32_bf16 v[14:17], v[110:113], v[180:183], v[14:17]
	v_mfma_f32_16x16x32_bf16 v[18:21], v[130:133], v[180:183], v[18:21]
	s_waitcnt lgkmcnt(0)
	v_mfma_f32_16x16x32_bf16 v[10:13], v[2:5], v[184:187], v[10:13]
	v_mfma_f32_16x16x32_bf16 v[14:17], v[114:117], v[184:187], v[14:17]
	v_mfma_f32_16x16x32_bf16 v[18:21], v[134:137], v[184:187], v[18:21]
	ds_read_b128 v[158:161], v162 offset:44800
	ds_read_b128 v[172:175], v162 offset:44864
	ds_read_b128 v[176:179], v162 offset:44928
	ds_read_b128 v[180:183], v162 offset:44992
	ds_read_b128 v[184:187], v162 offset:45056
	ds_read_b128 v[226:229], v162 offset:45120
	s_waitcnt lgkmcnt(5)
	v_mfma_f32_16x16x32_bf16 v[154:157], v[154:157], v[158:161], 0
	s_waitcnt lgkmcnt(4)
	v_mfma_f32_16x16x32_bf16 v[150:153], v[150:153], v[172:175], v[154:157]
	s_waitcnt lgkmcnt(3)
	v_mfma_f32_16x16x32_bf16 v[142:145], v[142:145], v[176:179], v[150:153]
	s_waitcnt lgkmcnt(2)
	v_mfma_f32_16x16x32_bf16 v[138:141], v[138:141], v[180:183], v[142:145]
	s_waitcnt lgkmcnt(1)
	v_mfma_f32_16x16x32_bf16 v[6:9], v[6:9], v[184:187], v[138:141]
	s_waitcnt lgkmcnt(0)
	v_mfma_f32_16x16x32_bf16 v[2:5], v[2:5], v[226:229], v[6:9]
	v_mfma_f32_16x16x32_bf16 v[6:9], v[22:25], v[158:161], 0
	v_mfma_f32_16x16x32_bf16 v[22:25], v[146:149], v[158:161], 0
	v_mfma_f32_16x16x32_bf16 v[6:9], v[98:101], v[172:175], v[6:9]
	v_mfma_f32_16x16x32_bf16 v[22:25], v[118:121], v[172:175], v[22:25]
	v_or_b32_e32 v174, 0x60, v168
	v_or_b32_e32 v172, 0x70, v168
	v_mfma_f32_16x16x32_bf16 v[6:9], v[102:105], v[176:179], v[6:9]
	v_mfma_f32_16x16x32_bf16 v[22:25], v[122:125], v[176:179], v[22:25]
	v_or_b32_e32 v178, 64, v168
	v_or_b32_e32 v176, 0x50, v168
	v_mfma_f32_16x16x32_bf16 v[6:9], v[106:109], v[180:183], v[6:9]
	v_mfma_f32_16x16x32_bf16 v[22:25], v[126:129], v[180:183], v[22:25]
	v_or_b32_e32 v182, 32, v168
	v_or_b32_e32 v180, 48, v168
	v_mfma_f32_16x16x32_bf16 v[6:9], v[110:113], v[184:187], v[6:9]
	v_mfma_f32_16x16x32_bf16 v[22:25], v[130:133], v[184:187], v[22:25]
	v_or_b32_e32 v184, 16, v168
	v_mfma_f32_16x16x32_bf16 v[6:9], v[114:117], v[226:229], v[6:9]
	v_mfma_f32_16x16x32_bf16 v[22:25], v[134:137], v[226:229], v[22:25]
	s_cbranch_vccnz .LBB0_318
	v_lshlrev_b32_e32 v98, 2, v221
	v_mov_b32_e32 v99, v1
	v_lshl_add_u64 v[98:99], s[92:93], 0, v[98:99]
	v_lshlrev_b64 v[100:101], 7, v[168:169]
	v_lshl_add_u64 v[100:101], v[98:99], 0, v[100:101]
	v_ashrrev_i32_e32 v185, 31, v184
	global_load_dwordx4 v[158:161], v[100:101], off
	global_load_dwordx4 v[154:157], v[100:101], off offset:64
	v_lshlrev_b64 v[100:101], 7, v[184:185]
	v_lshl_add_u64 v[100:101], v[98:99], 0, v[100:101]
	v_ashrrev_i32_e32 v183, 31, v182
	global_load_dwordx4 v[150:153], v[100:101], off
	global_load_dwordx4 v[146:149], v[100:101], off offset:64
	v_lshlrev_b64 v[100:101], 7, v[182:183]
	v_lshl_add_u64 v[100:101], v[98:99], 0, v[100:101]
	v_ashrrev_i32_e32 v181, 31, v180
	global_load_dwordx4 v[142:145], v[100:101], off
	global_load_dwordx4 v[138:141], v[100:101], off offset:64
	v_lshlrev_b64 v[100:101], 7, v[180:181]
	v_lshl_add_u64 v[100:101], v[98:99], 0, v[100:101]
	v_ashrrev_i32_e32 v179, 31, v178
	global_load_dwordx4 v[134:137], v[100:101], off
	global_load_dwordx4 v[130:133], v[100:101], off offset:64
	v_lshlrev_b64 v[100:101], 7, v[178:179]
	v_lshl_add_u64 v[100:101], v[98:99], 0, v[100:101]
	v_ashrrev_i32_e32 v177, 31, v176
	global_load_dwordx4 v[126:129], v[100:101], off
	global_load_dwordx4 v[122:125], v[100:101], off offset:64
	v_lshlrev_b64 v[100:101], 7, v[176:177]
	v_lshl_add_u64 v[100:101], v[98:99], 0, v[100:101]
	v_ashrrev_i32_e32 v175, 31, v174
	global_load_dwordx4 v[118:121], v[100:101], off
	global_load_dwordx4 v[114:117], v[100:101], off offset:64
	v_lshlrev_b64 v[100:101], 7, v[174:175]
	v_lshl_add_u64 v[100:101], v[98:99], 0, v[100:101]
	v_ashrrev_i32_e32 v173, 31, v172
	global_load_dwordx4 v[110:113], v[100:101], off
	global_load_dwordx4 v[106:109], v[100:101], off offset:64
	v_lshlrev_b64 v[100:101], 7, v[172:173]
	v_lshl_add_u64 v[98:99], v[98:99], 0, v[100:101]
	global_load_dwordx4 v[102:105], v[98:99], off
	s_nop 0
	global_load_dwordx4 v[98:101], v[98:99], off offset:64
	s_waitcnt vmcnt(0)
